# GEMM unit headers: accumulators cleared with 64 v_mov_b64 (inline 0) instead of 128 v_mov_b32 register copies
# speedup vs baseline: 1.0088x; 1.0088x over previous
.LBB0_277:
	s_ashr_i32 s43, s42, 31
	s_lshl_b64 s[38:39], s[42:43], 20
	s_add_u32 s40, s10, s38
	s_addc_u32 s41, s11, s39
	s_and_b64 s[38:39], s[4:5], exec
	s_cselect_b32 s43, s41, s9
	s_cselect_b32 s52, s40, s8
	s_ashr_i32 s45, s44, 31
	s_lshl_b64 s[38:39], s[44:45], 20
	s_add_u32 s70, s0, s38
	s_addc_u32 s71, s1, s39
	s_and_b64 s[38:39], s[4:5], exec
	s_cselect_b32 s45, s71, s7
	s_cselect_b32 s65, s70, s6
	s_add_u32 s66, s6, 0x100
	s_addc_u32 s67, s7, 0
	s_add_u32 s6, s8, 0x80080
	v_mov_b64_e32 v[8:9], 0
	s_addc_u32 s7, s9, 0
	s_mov_b32 s72, -2
	v_mov_b64_e32 v[10:11], 0
	v_mov_b64_e32 v[4:5], 0
	v_mov_b64_e32 v[6:7], 0
	v_mov_b64_e32 v[24:25], 0
	v_mov_b64_e32 v[26:27], 0
	v_mov_b64_e32 v[20:21], 0
	v_mov_b64_e32 v[22:23], 0
	v_mov_b64_e32 v[40:41], 0
	v_mov_b64_e32 v[42:43], 0
	v_mov_b64_e32 v[36:37], 0
	v_mov_b64_e32 v[38:39], 0
	v_mov_b64_e32 v[56:57], 0
	v_mov_b64_e32 v[58:59], 0
	v_mov_b64_e32 v[52:53], 0
	v_mov_b64_e32 v[54:55], 0
	v_mov_b64_e32 v[16:17], 0
	v_mov_b64_e32 v[18:19], 0
	v_mov_b64_e32 v[12:13], 0
	v_mov_b64_e32 v[14:15], 0
	v_mov_b64_e32 v[32:33], 0
	v_mov_b64_e32 v[34:35], 0
	v_mov_b64_e32 v[28:29], 0
	v_mov_b64_e32 v[30:31], 0
	v_mov_b64_e32 v[48:49], 0
	v_mov_b64_e32 v[50:51], 0
	v_mov_b64_e32 v[44:45], 0
	v_mov_b64_e32 v[46:47], 0
	v_mov_b64_e32 v[64:65], 0
	v_mov_b64_e32 v[66:67], 0
	v_mov_b64_e32 v[60:61], 0
	v_mov_b64_e32 v[62:63], 0
	v_mov_b64_e32 v[72:73], 0
	v_mov_b64_e32 v[74:75], 0
	v_mov_b64_e32 v[68:69], 0
	v_mov_b64_e32 v[70:71], 0
	v_mov_b64_e32 v[88:89], 0
	v_mov_b64_e32 v[90:91], 0
	v_mov_b64_e32 v[84:85], 0
	v_mov_b64_e32 v[86:87], 0
	v_mov_b64_e32 v[104:105], 0
	v_mov_b64_e32 v[106:107], 0
	v_mov_b64_e32 v[100:101], 0
	v_mov_b64_e32 v[102:103], 0
	v_mov_b64_e32 v[120:121], 0
	v_mov_b64_e32 v[122:123], 0
	v_mov_b64_e32 v[116:117], 0
	v_mov_b64_e32 v[118:119], 0
	v_mov_b64_e32 v[80:81], 0
	v_mov_b64_e32 v[82:83], 0
	v_mov_b64_e32 v[76:77], 0
	v_mov_b64_e32 v[78:79], 0
	v_mov_b64_e32 v[96:97], 0
	v_mov_b64_e32 v[98:99], 0
	v_mov_b64_e32 v[92:93], 0
	v_mov_b64_e32 v[94:95], 0
	v_mov_b64_e32 v[112:113], 0
	v_mov_b64_e32 v[114:115], 0
	v_mov_b64_e32 v[108:109], 0
	v_mov_b64_e32 v[110:111], 0
	v_mov_b64_e32 v[128:129], 0
	v_mov_b64_e32 v[130:131], 0
	v_mov_b64_e32 v[124:125], 0
	v_mov_b64_e32 v[126:127], 0

.LBB0_1228:
	s_ashr_i32 s13, s12, 31
	s_lshl_b64 s[14:15], s[12:13], 20
	s_add_u32 s14, s24, s14
	s_addc_u32 s15, s25, s15
	s_and_b64 s[16:17], s[4:5], exec
	s_cselect_b32 s13, s15, s21
	s_cselect_b32 s46, s14, s20
	s_ashr_i32 s11, s10, 31
	s_lshl_b64 s[16:17], s[10:11], 20
	s_add_u32 s16, s26, s16
	s_addc_u32 s17, s27, s17
	s_and_b64 s[22:23], s[4:5], exec
	s_cselect_b32 s11, s17, s19
	s_cselect_b32 s47, s16, s18
	s_add_u32 s48, s18, 0x100
	s_addc_u32 s49, s19, 0
	s_add_u32 s18, s20, 0x80080
	v_mov_b64_e32 v[4:5], 0
	s_addc_u32 s19, s21, 0
	s_mov_b32 s52, -2
	v_mov_b64_e32 v[6:7], 0
	v_mov_b64_e32 v[8:9], 0
	v_mov_b64_e32 v[10:11], 0
	v_mov_b64_e32 v[20:21], 0
	v_mov_b64_e32 v[22:23], 0
	v_mov_b64_e32 v[24:25], 0
	v_mov_b64_e32 v[26:27], 0
	v_mov_b64_e32 v[36:37], 0
	v_mov_b64_e32 v[38:39], 0
	v_mov_b64_e32 v[40:41], 0
	v_mov_b64_e32 v[42:43], 0
	v_mov_b64_e32 v[52:53], 0
	v_mov_b64_e32 v[54:55], 0
	v_mov_b64_e32 v[56:57], 0
	v_mov_b64_e32 v[58:59], 0
	v_mov_b64_e32 v[12:13], 0
	v_mov_b64_e32 v[14:15], 0
	v_mov_b64_e32 v[16:17], 0
	v_mov_b64_e32 v[18:19], 0
	v_mov_b64_e32 v[28:29], 0
	v_mov_b64_e32 v[30:31], 0
	v_mov_b64_e32 v[32:33], 0
	v_mov_b64_e32 v[34:35], 0
	v_mov_b64_e32 v[44:45], 0
	v_mov_b64_e32 v[46:47], 0
	v_mov_b64_e32 v[48:49], 0
	v_mov_b64_e32 v[50:51], 0
	v_mov_b64_e32 v[60:61], 0
	v_mov_b64_e32 v[62:63], 0
	v_mov_b64_e32 v[64:65], 0
	v_mov_b64_e32 v[66:67], 0
	s_waitcnt vmcnt(0)
	v_mov_b64_e32 v[68:69], 0
	v_mov_b64_e32 v[70:71], 0
	v_mov_b64_e32 v[72:73], 0
	v_mov_b64_e32 v[74:75], 0
	v_mov_b64_e32 v[84:85], 0
	v_mov_b64_e32 v[86:87], 0
	v_mov_b64_e32 v[88:89], 0
	v_mov_b64_e32 v[90:91], 0
	v_mov_b64_e32 v[100:101], 0
	v_mov_b64_e32 v[102:103], 0
	v_mov_b64_e32 v[104:105], 0
	v_mov_b64_e32 v[106:107], 0
	v_mov_b64_e32 v[116:117], 0
	v_mov_b64_e32 v[118:119], 0
	v_mov_b64_e32 v[120:121], 0
	v_mov_b64_e32 v[122:123], 0
	v_mov_b64_e32 v[76:77], 0
	v_mov_b64_e32 v[78:79], 0
	v_mov_b64_e32 v[80:81], 0
	v_mov_b64_e32 v[82:83], 0
	v_mov_b64_e32 v[92:93], 0
	v_mov_b64_e32 v[94:95], 0
	v_mov_b64_e32 v[96:97], 0
	v_mov_b64_e32 v[98:99], 0
	v_mov_b64_e32 v[108:109], 0
	v_mov_b64_e32 v[110:111], 0
	v_mov_b64_e32 v[112:113], 0
	v_mov_b64_e32 v[114:115], 0
	v_mov_b64_e32 v[124:125], 0
	v_mov_b64_e32 v[126:127], 0
	v_mov_b64_e32 v[128:129], 0
	v_mov_b64_e32 v[130:131], 0

.LBB0_1335:
	s_ashr_i32 s81, s80, 31
	s_lshl_b64 s[8:9], s[80:81], 20
	s_add_u32 s82, s56, s8
	s_addc_u32 s83, s57, s9
	s_and_b64 s[8:9], s[6:7], exec
	s_cselect_b32 s18, s83, s17
	s_cselect_b32 s19, s82, s16
	s_ashr_i32 s39, s38, 31
	s_lshl_b64 s[8:9], s[38:39], 20
	s_add_u32 s84, s94, s8
	s_addc_u32 s85, s95, s9
	s_and_b64 s[8:9], s[6:7], exec
	s_cselect_b32 s22, s85, s15
	s_cselect_b32 s23, s84, s14
	s_add_u32 s39, s14, 0x100
	s_addc_u32 s40, s15, 0
	s_add_u32 s8, s16, 0x80080
	v_mov_b64_e32 v[4:5], 0
	s_addc_u32 s9, s17, 0
	s_mov_b32 s16, -2
	v_mov_b64_e32 v[6:7], 0
	s_waitcnt vmcnt(0)
	v_and_b32_e32 v250, 15, v0
	v_mov_b32_e32 v251, s12
	v_add_u32_e32 v250, s63, v250
	v_lshl_add_u32 v250, v251, 8, v250
	v_lshlrev_b32_e32 v250, 2, v250
	global_load_dword v242, v250, s[24:25]
	global_load_dword v243, v250, s[24:25] offset:64
	global_load_dword v244, v250, s[24:25] offset:128
	global_load_dword v245, v250, s[24:25] offset:192
	global_load_dword v246, v250, s[24:25] offset:512
	global_load_dword v247, v250, s[24:25] offset:576
	global_load_dword v248, v250, s[24:25] offset:640
	global_load_dword v249, v250, s[24:25] offset:704
	v_mov_b64_e32 v[68:69], 0
	v_mov_b64_e32 v[70:71], 0
	v_mov_b64_e32 v[12:13], 0
	v_mov_b64_e32 v[14:15], 0
	v_mov_b64_e32 v[76:77], 0
	v_mov_b64_e32 v[78:79], 0
	v_mov_b64_e32 v[20:21], 0
	v_mov_b64_e32 v[22:23], 0
	v_mov_b64_e32 v[84:85], 0
	v_mov_b64_e32 v[86:87], 0
	v_mov_b64_e32 v[60:61], 0
	v_mov_b64_e32 v[62:63], 0
	v_mov_b64_e32 v[124:125], 0
	v_mov_b64_e32 v[126:127], 0
	v_mov_b64_e32 v[8:9], 0
	v_mov_b64_e32 v[10:11], 0
	v_mov_b64_e32 v[72:73], 0
	v_mov_b64_e32 v[74:75], 0
	v_mov_b64_e32 v[16:17], 0
	v_mov_b64_e32 v[18:19], 0
	v_mov_b64_e32 v[80:81], 0
	v_mov_b64_e32 v[82:83], 0
	v_mov_b64_e32 v[24:25], 0
	v_mov_b64_e32 v[26:27], 0
	v_mov_b64_e32 v[88:89], 0
	v_mov_b64_e32 v[90:91], 0
	v_mov_b64_e32 v[64:65], 0
	v_mov_b64_e32 v[66:67], 0
	v_mov_b64_e32 v[128:129], 0
	v_mov_b64_e32 v[130:131], 0
	v_mov_b64_e32 v[132:133], 0
	v_mov_b64_e32 v[134:135], 0
	v_mov_b64_e32 v[164:165], 0
	v_mov_b64_e32 v[166:167], 0
	v_mov_b64_e32 v[140:141], 0
	v_mov_b64_e32 v[142:143], 0
	v_mov_b64_e32 v[172:173], 0
	v_mov_b64_e32 v[174:175], 0
	v_mov_b64_e32 v[148:149], 0
	v_mov_b64_e32 v[150:151], 0
	v_mov_b64_e32 v[184:185], 0
	v_mov_b64_e32 v[186:187], 0
	v_mov_b64_e32 v[156:157], 0
	v_mov_b64_e32 v[158:159], 0
	v_mov_b64_e32 v[180:181], 0
	v_mov_b64_e32 v[182:183], 0
	v_mov_b64_e32 v[136:137], 0
	v_mov_b64_e32 v[138:139], 0
	v_mov_b64_e32 v[168:169], 0
	v_mov_b64_e32 v[170:171], 0
	v_mov_b64_e32 v[144:145], 0
	v_mov_b64_e32 v[146:147], 0
	v_mov_b64_e32 v[176:177], 0
	v_mov_b64_e32 v[178:179], 0
	v_mov_b64_e32 v[152:153], 0
	v_mov_b64_e32 v[154:155], 0
	v_mov_b64_e32 v[188:189], 0
	v_mov_b64_e32 v[190:191], 0
	v_mov_b64_e32 v[160:161], 0
	v_mov_b64_e32 v[162:163], 0
	v_mov_b64_e32 v[192:193], 0
	v_mov_b64_e32 v[194:195], 0
	s_mov_b64 s[20:21], 0x80

.LBB0_1503:
	s_add_u32 s52, s24, 0x100
	v_mov_b64_e32 v[4:5], 0
	s_addc_u32 s56, s25, 0
	s_mov_b32 s57, -2
	v_mov_b64_e32 v[6:7], 0
	v_mov_b64_e32 v[8:9], 0
	v_mov_b64_e32 v[10:11], 0
	v_mov_b64_e32 v[20:21], 0
	v_mov_b64_e32 v[22:23], 0
	v_mov_b64_e32 v[24:25], 0
	v_mov_b64_e32 v[26:27], 0
	v_mov_b64_e32 v[36:37], 0
	v_mov_b64_e32 v[38:39], 0
	v_mov_b64_e32 v[40:41], 0
	v_mov_b64_e32 v[42:43], 0
	v_mov_b64_e32 v[52:53], 0
	v_mov_b64_e32 v[54:55], 0
	v_mov_b64_e32 v[56:57], 0
	v_mov_b64_e32 v[58:59], 0
	v_mov_b64_e32 v[12:13], 0
	v_mov_b64_e32 v[14:15], 0
	v_mov_b64_e32 v[16:17], 0
	v_mov_b64_e32 v[18:19], 0
	v_mov_b64_e32 v[28:29], 0
	v_mov_b64_e32 v[30:31], 0
	v_mov_b64_e32 v[32:33], 0
	v_mov_b64_e32 v[34:35], 0
	v_mov_b64_e32 v[44:45], 0
	v_mov_b64_e32 v[46:47], 0
	v_mov_b64_e32 v[48:49], 0
	v_mov_b64_e32 v[50:51], 0
	v_mov_b64_e32 v[60:61], 0
	v_mov_b64_e32 v[62:63], 0
	v_mov_b64_e32 v[64:65], 0
	v_mov_b64_e32 v[66:67], 0
	s_waitcnt vmcnt(0)
	v_mov_b64_e32 v[68:69], 0
	v_mov_b64_e32 v[70:71], 0
	v_mov_b64_e32 v[72:73], 0
	v_mov_b64_e32 v[74:75], 0
	v_mov_b64_e32 v[84:85], 0
	v_mov_b64_e32 v[86:87], 0
	v_mov_b64_e32 v[88:89], 0
	v_mov_b64_e32 v[90:91], 0
	v_mov_b64_e32 v[100:101], 0
	v_mov_b64_e32 v[102:103], 0
	v_mov_b64_e32 v[104:105], 0
	v_mov_b64_e32 v[106:107], 0
	v_mov_b64_e32 v[116:117], 0
	v_mov_b64_e32 v[118:119], 0
	v_mov_b64_e32 v[120:121], 0
	v_mov_b64_e32 v[122:123], 0
	v_mov_b64_e32 v[76:77], 0
	v_mov_b64_e32 v[78:79], 0
	v_mov_b64_e32 v[80:81], 0
	v_mov_b64_e32 v[82:83], 0
	v_mov_b64_e32 v[92:93], 0
	v_mov_b64_e32 v[94:95], 0
	v_mov_b64_e32 v[96:97], 0
	v_mov_b64_e32 v[98:99], 0
	v_mov_b64_e32 v[108:109], 0
	v_mov_b64_e32 v[110:111], 0
	v_mov_b64_e32 v[112:113], 0
	v_mov_b64_e32 v[114:115], 0
	v_mov_b64_e32 v[140:141], 0
	v_mov_b64_e32 v[142:143], 0
	v_mov_b64_e32 v[144:145], 0
	v_mov_b64_e32 v[146:147], 0
